# grid-barrier poll loop sleeps longer (s_sleep 5) so idle workgroups stop slowing the straggler workgroups; on top of GEMM wait/epilogue and dn_scan LDS-read hoisting edits
# speedup vs baseline: 1.0797x; 1.0479x over previous
; __global__ void __launch_bounds__(256, 2) mega(P p, int ph_lo, int ph_hi) {
;     ...
;   cg::grid_group grid = cg::this_grid();
;   run_phase(p, 0, smem, &s_item);
;   grid.sync();
.LBB0_94:
	s_sleep 5
	global_load_dword v3, v0, s[4:5] offset:32 sc1
	s_waitcnt vmcnt(0)
	v_and_b32_e32 v3, 0xffff0000, v3
	v_cmp_ne_u32_e32 vcc, v3, v2
	s_or_b64 s[6:7], vcc, s[6:7]
	s_andn2_b64 exec, exec, s[6:7]
	s_cbranch_execnz .LBB0_94

; __global__ void __launch_bounds__(256, 2) mega(P p, int ph_lo, int ph_hi) {
;     ...
;       grid.sync();
.LBB0_1065:
	s_sleep 5
	global_load_dword v1, v177, s[2:3] offset:32 sc1
	s_waitcnt vmcnt(0)
	v_and_b32_e32 v1, 0xffff0000, v1
	v_cmp_ne_u32_e32 vcc, v1, v0
	s_or_b64 s[4:5], vcc, s[4:5]
	s_andn2_b64 exec, exec, s[4:5]
	s_cbranch_execnz .LBB0_1065
	s_getpc_b64 s[98:99]
